# forget-gate phase: LDS table fill loop hand-unrolled so its 16 loads per thread are in flight together instead of one round trip each
# baseline (speedup 1.0000x reference)
; #define LAS __attribute__((address_space(3)))
; __global__ void __launch_bounds__(NTHREADS, 2) fwd_megakernel(Args args) {
;     ...
;                 { const f32x4* wsrc = (const f32x4*)(wf_tab + (size_t)j * NH * DM);
;                   for (int idx = tid; idx < NH * DM / 4; idx += NTHREADS) ((LAS f32x4*)wfl)[idx] = wsrc[idx]; }
.LBB0_245:
	s_mov_b64 s[12:13], 0x2000
	global_load_dwordx4 v[6:9], v[2:3], off
	v_lshl_add_u64 v[2:3], v[2:3], 0, s[12:13]
	global_load_dwordx4 v[10:13], v[2:3], off
	v_lshl_add_u64 v[2:3], v[2:3], 0, s[12:13]
	global_load_dwordx4 v[14:17], v[2:3], off
	v_lshl_add_u64 v[2:3], v[2:3], 0, s[12:13]
	global_load_dwordx4 v[18:21], v[2:3], off
	v_lshl_add_u64 v[2:3], v[2:3], 0, s[12:13]
	global_load_dwordx4 v[22:25], v[2:3], off
	v_lshl_add_u64 v[2:3], v[2:3], 0, s[12:13]
	global_load_dwordx4 v[26:29], v[2:3], off
	v_lshl_add_u64 v[2:3], v[2:3], 0, s[12:13]
	global_load_dwordx4 v[30:33], v[2:3], off
	v_lshl_add_u64 v[2:3], v[2:3], 0, s[12:13]
	global_load_dwordx4 v[34:37], v[2:3], off
	v_lshl_add_u64 v[2:3], v[2:3], 0, s[12:13]
	global_load_dwordx4 v[38:41], v[2:3], off
	v_lshl_add_u64 v[2:3], v[2:3], 0, s[12:13]
	global_load_dwordx4 v[42:45], v[2:3], off
	v_lshl_add_u64 v[2:3], v[2:3], 0, s[12:13]
	global_load_dwordx4 v[46:49], v[2:3], off
	v_lshl_add_u64 v[2:3], v[2:3], 0, s[12:13]
	global_load_dwordx4 v[50:53], v[2:3], off
	v_lshl_add_u64 v[2:3], v[2:3], 0, s[12:13]
	global_load_dwordx4 v[54:57], v[2:3], off
	v_lshl_add_u64 v[2:3], v[2:3], 0, s[12:13]
	global_load_dwordx4 v[58:61], v[2:3], off
	v_lshl_add_u64 v[2:3], v[2:3], 0, s[12:13]
	global_load_dwordx4 v[62:65], v[2:3], off
	v_lshl_add_u64 v[2:3], v[2:3], 0, s[12:13]
	global_load_dwordx4 v[66:69], v[2:3], off
	s_waitcnt vmcnt(15)
	ds_write_b128 v1, v[6:9]
	s_waitcnt vmcnt(14)
	ds_write_b128 v1, v[10:13] offset:8192
	s_waitcnt vmcnt(13)
	ds_write_b128 v1, v[14:17] offset:16384
	s_waitcnt vmcnt(12)
	ds_write_b128 v1, v[18:21] offset:24576
	s_waitcnt vmcnt(11)
	ds_write_b128 v1, v[22:25] offset:32768
	s_waitcnt vmcnt(10)
	ds_write_b128 v1, v[26:29] offset:40960
	s_waitcnt vmcnt(9)
	ds_write_b128 v1, v[30:33] offset:49152
	s_waitcnt vmcnt(8)
	ds_write_b128 v1, v[34:37] offset:57344
	v_add_u32_e32 v1, 0x10000, v1
	s_waitcnt vmcnt(7)
	ds_write_b128 v1, v[38:41]
	s_waitcnt vmcnt(6)
	ds_write_b128 v1, v[42:45] offset:8192
	s_waitcnt vmcnt(5)
	ds_write_b128 v1, v[46:49] offset:16384
	s_waitcnt vmcnt(4)
	ds_write_b128 v1, v[50:53] offset:24576
	s_waitcnt vmcnt(3)
	ds_write_b128 v1, v[54:57] offset:32768
	s_waitcnt vmcnt(2)
	ds_write_b128 v1, v[58:61] offset:40960
	s_waitcnt vmcnt(1)
	ds_write_b128 v1, v[62:65] offset:49152
	s_waitcnt vmcnt(0)
	ds_write_b128 v1, v[66:69] offset:57344
